# attention block epilogue rewritten: DPP lane exchange instead of ds_bpermute, convert all then 64 stores under one exec mask (on top of barrier v2 + sc1 stores)
# baseline (speedup 1.0000x reference)
; __device__ __forceinline__ void partialSM(f32x16& p0, f32x16& p1, float& m_reg, float& mn, float& alpha, bool rs) {
;     ...
;     const float mnL = rs ? -mn * C2 : -__builtin_inff();
;     for (int r = 0; r < 16; ++r) p0[r] = fmaf(p0[r], C2, mnL); for (int r = 0; r < 16; ++r) p1[r] = fmaf(p1[r], C2, mnL);
;     for (int r = 0; r < 16; ++r) p0[r] = __builtin_amdgcn_exp2f(p0[r]);
; }
; __device__ __forceinline__ void finishSM(f32x16& p0, f32x16& p1, float alpha, float& l_reg, bf16x8& pa0, bf16x8& pa1, bf16x8& pa2, bf16x8& pa3) {
;     for (int r = 0; r < 16; ++r) p1[r] = __builtin_amdgcn_exp2f(p1[r]);
;     float ps = 0; for (int r = 0; r < 16; ++r) ps += p0[r]; for (int r = 0; r < 16; ++r) ps += p1[r];
;     { auto rr = __builtin_amdgcn_permlane32_swap(__float_as_uint(ps), __float_as_uint(ps), false, false);
;       ps = __uint_as_float(rr[0]) + __uint_as_float(rr[1]); }
;     l_reg = l_reg * alpha + ps;
;     ...
;     PK4(p0, 0, pa0); PK4(p0, 8, pa1); PK4(p1, 0, pa2); PK4(p1, 8, pa3);
;     ...
; }
; template <int VB>
; __device__ __forceinline__ void pv_tile(f32x16* o, int vb0, bf16x8 pa0, bf16x8 pa1, bf16x8 pa2, bf16x8 pa3) {
;     ...
;     PV_D0(0); PV_D0(1); PV_D0(2); PV_D0(3);
;     ...
; }
.LBB0_113:
	v_cndmask_b32_e64 v106, v106, v198, s[40:41]
	v_mul_f32_e32 v106, 0xbe0293ee, v106
	v_fmamk_f32 v107, v66, 0x3e0293ee, v106
	v_fmamk_f32 v152, v67, 0x3e0293ee, v106
	v_fmamk_f32 v158, v81, 0x3e0293ee, v106
	v_exp_f32_e32 v81, v107
	v_fmamk_f32 v68, v68, 0x3e0293ee, v106
	v_fmamk_f32 v67, v83, 0x3e0293ee, v106
	v_exp_f32_e32 v83, v152
	v_fmamk_f32 v69, v69, 0x3e0293ee, v106
	v_fmamk_f32 v156, v79, 0x3e0293ee, v106
	v_exp_f32_e32 v79, v68
	v_fmamk_f32 v70, v70, 0x3e0293ee, v106
	v_fmamk_f32 v66, v82, 0x3e0293ee, v106
	v_exp_f32_e32 v82, v69
	v_fmamk_f32 v71, v71, 0x3e0293ee, v106
	v_fmamk_f32 v72, v72, 0x3e0293ee, v106
	v_fmamk_f32 v73, v73, 0x3e0293ee, v106
	v_fmamk_f32 v74, v74, 0x3e0293ee, v106
	v_fmamk_f32 v75, v75, 0x3e0293ee, v106
	v_fmamk_f32 v153, v76, 0x3e0293ee, v106
	v_fmamk_f32 v154, v77, 0x3e0293ee, v106
	v_fmamk_f32 v155, v78, 0x3e0293ee, v106
	v_fmamk_f32 v157, v80, 0x3e0293ee, v106
	v_fmamk_f32 v84, v84, 0x3e0293ee, v106
	v_fmamk_f32 v85, v85, 0x3e0293ee, v106
	v_fmamk_f32 v86, v86, 0x3e0293ee, v106
	v_fmamk_f32 v87, v87, 0x3e0293ee, v106
	v_fmamk_f32 v88, v88, 0x3e0293ee, v106
	v_fmamk_f32 v89, v89, 0x3e0293ee, v106
	v_fmamk_f32 v90, v90, 0x3e0293ee, v106
	v_fmamk_f32 v91, v91, 0x3e0293ee, v106
	v_fmamk_f32 v92, v92, 0x3e0293ee, v106
	v_fmamk_f32 v93, v93, 0x3e0293ee, v106
	v_fmamk_f32 v94, v94, 0x3e0293ee, v106
	v_exp_f32_e32 v77, v70
	v_fmamk_f32 v95, v95, 0x3e0293ee, v106
	v_fmamk_f32 v96, v96, 0x3e0293ee, v106
	v_fmac_f32_e32 v106, 0x3e0293ee, v97
	v_exp_f32_e32 v97, v66
	v_add_f32_e32 v66, 0, v81
	v_exp_f32_e32 v80, v71
	v_add_f32_e32 v66, v83, v66
	v_exp_f32_e32 v76, v72
	v_add_f32_e32 v66, v79, v66
	v_exp_f32_e32 v78, v73
	v_add_f32_e32 v66, v82, v66
	v_exp_f32_e32 v73, v74
	v_add_f32_e32 v66, v77, v66
	v_exp_f32_e32 v75, v75
	v_add_f32_e32 v66, v80, v66
	v_exp_f32_e32 v71, v153
	v_add_f32_e32 v66, v76, v66
	v_exp_f32_e32 v74, v154
	v_add_f32_e32 v66, v78, v66
	v_exp_f32_e32 v69, v155
	v_add_f32_e32 v66, v73, v66
	v_exp_f32_e32 v72, v156
	v_add_f32_e32 v66, v75, v66
	v_exp_f32_e32 v68, v157
	v_add_f32_e32 v66, v71, v66
	v_exp_f32_e32 v70, v158
	v_add_f32_e32 v66, v74, v66
	v_add_f32_e32 v66, v69, v66
	v_exp_f32_e32 v107, v67
	v_add_f32_e32 v66, v72, v66
	v_exp_f32_e32 v152, v84
	v_add_f32_e32 v66, v68, v66
	v_exp_f32_e32 v153, v85
	v_add_f32_e32 v66, v70, v66
	v_exp_f32_e32 v154, v86
	v_add_f32_e32 v66, v97, v66
	v_exp_f32_e32 v155, v87
	v_add_f32_e32 v66, v107, v66
	v_exp_f32_e32 v88, v88
	v_add_f32_e32 v66, v152, v66
	v_exp_f32_e32 v89, v89
	v_add_f32_e32 v66, v153, v66
	v_exp_f32_e32 v90, v90
	v_add_f32_e32 v66, v154, v66
	v_exp_f32_e32 v91, v91
	v_add_f32_e32 v66, v155, v66
	v_exp_f32_e32 v92, v92
	v_add_f32_e32 v66, v88, v66
	v_exp_f32_e32 v93, v93
	v_add_f32_e32 v66, v89, v66
	v_exp_f32_e32 v94, v94
	v_add_f32_e32 v66, v90, v66
	v_exp_f32_e32 v95, v95
	v_add_f32_e32 v66, v91, v66
	v_exp_f32_e32 v96, v96
	v_add_f32_e32 v66, v92, v66
	v_exp_f32_e32 v106, v106
	v_add_f32_e32 v66, v93, v66
	v_add_f32_e32 v66, v94, v66
	v_add_f32_e32 v66, v95, v66
	v_add_f32_e32 v66, v96, v66
	v_add_f32_e32 v66, v106, v66
	v_mov_b32_e32 v67, v66
	s_nop 1
	v_permlane32_swap_b32_e32 v66, v67
	v_cvt_pk_bf16_f32 v84, v81, v83
	v_cvt_pk_bf16_f32 v85, v79, v82
	v_cvt_pk_bf16_f32 v86, v77, v80
	v_cvt_pk_bf16_f32 v87, v76, v78
	v_cvt_pk_bf16_f32 v76, v73, v75
	v_cvt_pk_bf16_f32 v77, v71, v74
	v_cvt_pk_bf16_f32 v78, v69, v72
	v_cvt_pk_bf16_f32 v79, v68, v70
	v_cvt_pk_bf16_f32 v68, v97, v107
	v_cvt_pk_bf16_f32 v69, v152, v153
	v_cvt_pk_bf16_f32 v70, v154, v155
	v_cvt_pk_bf16_f32 v71, v88, v89
	v_cvt_pk_bf16_f32 v72, v90, v91
	v_cvt_pk_bf16_f32 v73, v92, v93
	v_cvt_pk_bf16_f32 v74, v94, v95
	v_cvt_pk_bf16_f32 v75, v96, v106
	s_nop 0
	v_permlane32_swap_b32_e32 v84, v86
	v_permlane32_swap_b32_e32 v85, v87
	v_permlane32_swap_b32_e32 v76, v78
	v_permlane32_swap_b32_e32 v77, v79
	v_permlane32_swap_b32_e32 v68, v70
	v_permlane32_swap_b32_e32 v69, v71
	v_permlane32_swap_b32_e32 v72, v74
	v_permlane32_swap_b32_e32 v73, v75
	ds_read_b64_tr_b16 v[80:81], v185 offset:0x4000
	ds_read_b64_tr_b16 v[82:83], v185 offset:0x4800
	ds_read_b64_tr_b16 v[88:89], v185 offset:0x5000
	ds_read_b64_tr_b16 v[90:91], v185 offset:0x5800
	ds_read_b64_tr_b16 v[92:93], v185 offset:0x6000
	ds_read_b64_tr_b16 v[94:95], v185 offset:0x6800
	ds_read_b64_tr_b16 v[152:153], v185 offset:0x7000
	ds_read_b64_tr_b16 v[154:155], v185 offset:0x7800
	s_waitcnt lgkmcnt(0)
	s_nop 0
	v_mfma_f32_32x32x16_bf16 v[50:65], v[84:87], v[80:83], v[50:65]
	ds_read_b64_tr_b16 v[80:81], v185 offset:0x4200
	ds_read_b64_tr_b16 v[82:83], v185 offset:0x4a00
	v_mfma_f32_32x32x16_bf16 v[50:65], v[76:79], v[88:91], v[50:65]
	ds_read_b64_tr_b16 v[88:89], v185 offset:0x5200
	ds_read_b64_tr_b16 v[90:91], v185 offset:0x5a00
	v_mfma_f32_32x32x16_bf16 v[50:65], v[68:71], v[92:95], v[50:65]
	ds_read_b64_tr_b16 v[92:93], v185 offset:0x6200
	ds_read_b64_tr_b16 v[94:95], v185 offset:0x6a00
	v_mfma_f32_32x32x16_bf16 v[50:65], v[72:75], v[152:155], v[50:65]
	ds_read_b64_tr_b16 v[152:153], v185 offset:0x7200
	ds_read_b64_tr_b16 v[154:155], v185 offset:0x7a00
	s_waitcnt lgkmcnt(0)
	v_mfma_f32_32x32x16_bf16 v[34:49], v[84:87], v[80:83], v[34:49]
	ds_read_b64_tr_b16 v[80:81], v185 offset:0x4400
	ds_read_b64_tr_b16 v[82:83], v185 offset:0x4c00
	v_mfma_f32_32x32x16_bf16 v[34:49], v[76:79], v[88:91], v[34:49]
	ds_read_b64_tr_b16 v[88:89], v185 offset:0x5400
	ds_read_b64_tr_b16 v[90:91], v185 offset:0x5c00
	v_mfma_f32_32x32x16_bf16 v[34:49], v[68:71], v[92:95], v[34:49]
	ds_read_b64_tr_b16 v[92:93], v185 offset:0x6400
	ds_read_b64_tr_b16 v[94:95], v185 offset:0x6c00
	v_mfma_f32_32x32x16_bf16 v[34:49], v[72:75], v[152:155], v[34:49]
	ds_read_b64_tr_b16 v[152:153], v185 offset:0x7400
	ds_read_b64_tr_b16 v[154:155], v185 offset:0x7c00
	s_waitcnt lgkmcnt(0)
; __device__ __forceinline__ int crow(int r, int hi) { return (r & 3) + 8 * (r >> 2) + 4 * hi; }
; __device__ __forceinline__ unsigned cvtpk(float lo, float hi) { unsigned r; asm volatile("v_cvt_pk_bf16_f32 %0, %1, %2" : "=v"(r) : "v"(lo), "v"(hi)); return r; }
; __device__ __forceinline__ void moba_block(const BlockRef& cur, const BlockRef& nxt, char* lds, Seam& S) {
;     ...
;     if (hi == 0) li_l[r32] = l_reg; asm volatile("s_waitcnt lgkmcnt(0)" ::: "memory");
;     float rli[16];
; #pragma unroll
;     for (int r = 0; r < 16; ++r) rli[r] = __builtin_amdgcn_rcpf(li_l[crow(r, hi)]);
;     bf16* Ow = cur.O + (size_t)(wid * QBLK) * OSTR;
; #pragma unroll
;     for (int r = 0; r < 16; ++r) { const int orow = crow(r, hi);
; #pragma unroll
;         for (int d0 = 0; d0 < 4; ++d0) { const float v = o[d0][r] * rli[r];
;             const float vn = __shfl_xor(v, 1);
;             if ((r32 & 1) == 0) *(unsigned*)(Ow + (size_t)orow * OSTR + d0 * 32 + r32) = cvtpk(v, vn); } }
	v_mfma_f32_32x32x16_bf16 v[18:33], v[84:87], v[80:83], v[18:33]
	ds_read_b64_tr_b16 v[80:81], v185 offset:0x4600
	ds_read_b64_tr_b16 v[82:83], v185 offset:0x4e00
	v_mfma_f32_32x32x16_bf16 v[18:33], v[76:79], v[88:91], v[18:33]
	ds_read_b64_tr_b16 v[88:89], v185 offset:0x5600
	ds_read_b64_tr_b16 v[90:91], v185 offset:0x5e00
	v_mfma_f32_32x32x16_bf16 v[18:33], v[68:71], v[92:95], v[18:33]
	ds_read_b64_tr_b16 v[92:93], v185 offset:0x6600
	ds_read_b64_tr_b16 v[94:95], v185 offset:0x6e00
	v_mfma_f32_32x32x16_bf16 v[18:33], v[72:75], v[152:155], v[18:33]
	ds_read_b64_tr_b16 v[152:153], v185 offset:0x7600
	ds_read_b64_tr_b16 v[154:155], v185 offset:0x7e00
	s_waitcnt lgkmcnt(0)
	v_mfma_f32_32x32x16_bf16 v[2:17], v[84:87], v[80:83], v[2:17]
	v_mfma_f32_32x32x16_bf16 v[2:17], v[76:79], v[88:91], v[2:17]
	v_mfma_f32_32x32x16_bf16 v[2:17], v[68:71], v[92:95], v[2:17]
	v_mfma_f32_32x32x16_bf16 v[2:17], v[72:75], v[152:155], v[2:17]
	s_waitcnt vmcnt(8)
	s_waitcnt vmcnt(9)
	ds_write_b128 v188, v[144:147] offset:32768
	s_waitcnt vmcnt(8)
	ds_write_b128 v188, v[148:151] offset:40960
	s_and_saveexec_b64 s[0:1], s[38:39]
	v_add_f32_e32 v68, v98, v104
	v_fmac_f32_e32 v68, v189, v201
	v_add_f32_e32 v66, v66, v67
	v_fmac_f32_e32 v66, v68, v105
	ds_write_b32 v187, v66
	s_or_b64 exec, exec, s[0:1]
	s_waitcnt lgkmcnt(0)
	ds_read_b128 v[78:81], v186
	ds_read_b128 v[74:77], v186 offset:32
	s_ashr_i32 s95, s94, 31
	ds_read_b128 v[70:73], v186 offset:64
	ds_read_b128 v[66:69], v186 offset:96
	s_lshl_b64 s[0:1], s[94:95], 11
	s_add_u32 s0, s92, s0
	s_addc_u32 s1, s93, s1
	v_and_b32_e32 v82, 1, v183
	v_lshlrev_b32_e32 v98, 1, v184
	v_cmp_eq_u32_e64 s[38:39], 0, v82
	v_lshl_add_u64 v[82:83], s[0:1], 0, v[98:99]
	v_lshlrev_b32_e32 v98, 13, v182
	v_lshl_add_u64 v[82:83], v[82:83], 0, v[98:99]
	s_waitcnt lgkmcnt(0)
	v_rcp_f32_e32 v78, v78
	v_rcp_f32_e32 v79, v79
	v_rcp_f32_e32 v80, v80
	v_rcp_f32_e32 v81, v81
	v_rcp_f32_e32 v74, v74
	v_rcp_f32_e32 v75, v75
	v_rcp_f32_e32 v76, v76
	v_rcp_f32_e32 v77, v77
	v_rcp_f32_e32 v70, v70
	v_rcp_f32_e32 v71, v71
	v_rcp_f32_e32 v72, v72
	v_rcp_f32_e32 v73, v73
	v_rcp_f32_e32 v66, v66
	v_rcp_f32_e32 v67, v67
	v_rcp_f32_e32 v68, v68
	v_rcp_f32_e32 v69, v69
	s_nop 0
	v_mul_f32_e32 v50, v50, v78
	v_mul_f32_e32 v34, v34, v78
	v_mul_f32_e32 v18, v18, v78
	v_mul_f32_e32 v2, v2, v78
	v_mul_f32_e32 v51, v51, v79
	v_mul_f32_e32 v35, v35, v79
	v_mul_f32_e32 v19, v19, v79
	v_mul_f32_e32 v3, v3, v79
	v_mov_b32_dpp v86, v50 quad_perm:[1,0,3,2] row_mask:0xf bank_mask:0xf
	v_mov_b32_dpp v87, v34 quad_perm:[1,0,3,2] row_mask:0xf bank_mask:0xf
	v_mov_b32_dpp v88, v18 quad_perm:[1,0,3,2] row_mask:0xf bank_mask:0xf
	v_mov_b32_dpp v89, v2 quad_perm:[1,0,3,2] row_mask:0xf bank_mask:0xf
	v_mov_b32_dpp v90, v51 quad_perm:[1,0,3,2] row_mask:0xf bank_mask:0xf
	v_mov_b32_dpp v91, v35 quad_perm:[1,0,3,2] row_mask:0xf bank_mask:0xf
	v_mov_b32_dpp v92, v19 quad_perm:[1,0,3,2] row_mask:0xf bank_mask:0xf
	v_mov_b32_dpp v93, v3 quad_perm:[1,0,3,2] row_mask:0xf bank_mask:0xf
	v_cvt_pk_bf16_f32 v50, v50, v86
	v_cvt_pk_bf16_f32 v34, v34, v87
	v_cvt_pk_bf16_f32 v18, v18, v88
	v_cvt_pk_bf16_f32 v2, v2, v89
	v_cvt_pk_bf16_f32 v51, v51, v90
	v_cvt_pk_bf16_f32 v35, v35, v91
	v_cvt_pk_bf16_f32 v19, v19, v92
	v_cvt_pk_bf16_f32 v3, v3, v93
	v_mul_f32_e32 v52, v52, v80
	v_mul_f32_e32 v36, v36, v80
	v_mul_f32_e32 v20, v20, v80
	v_mul_f32_e32 v4, v4, v80
	v_mul_f32_e32 v53, v53, v81
	v_mul_f32_e32 v37, v37, v81
	v_mul_f32_e32 v21, v21, v81
	v_mul_f32_e32 v5, v5, v81
	v_mov_b32_dpp v86, v52 quad_perm:[1,0,3,2] row_mask:0xf bank_mask:0xf
	v_mov_b32_dpp v87, v36 quad_perm:[1,0,3,2] row_mask:0xf bank_mask:0xf
	v_mov_b32_dpp v88, v20 quad_perm:[1,0,3,2] row_mask:0xf bank_mask:0xf
	v_mov_b32_dpp v89, v4 quad_perm:[1,0,3,2] row_mask:0xf bank_mask:0xf
	v_mov_b32_dpp v90, v53 quad_perm:[1,0,3,2] row_mask:0xf bank_mask:0xf
	v_mov_b32_dpp v91, v37 quad_perm:[1,0,3,2] row_mask:0xf bank_mask:0xf
	v_mov_b32_dpp v92, v21 quad_perm:[1,0,3,2] row_mask:0xf bank_mask:0xf
	v_mov_b32_dpp v93, v5 quad_perm:[1,0,3,2] row_mask:0xf bank_mask:0xf
	v_cvt_pk_bf16_f32 v52, v52, v86
	v_cvt_pk_bf16_f32 v36, v36, v87
	v_cvt_pk_bf16_f32 v20, v20, v88
	v_cvt_pk_bf16_f32 v4, v4, v89
	v_cvt_pk_bf16_f32 v53, v53, v90
	v_cvt_pk_bf16_f32 v37, v37, v91
	v_cvt_pk_bf16_f32 v21, v21, v92
	v_cvt_pk_bf16_f32 v5, v5, v93
	v_mul_f32_e32 v54, v54, v74
	v_mul_f32_e32 v38, v38, v74
	v_mul_f32_e32 v22, v22, v74
	v_mul_f32_e32 v6, v6, v74
	v_mul_f32_e32 v55, v55, v75
	v_mul_f32_e32 v39, v39, v75
	v_mul_f32_e32 v23, v23, v75
	v_mul_f32_e32 v7, v7, v75
	v_mov_b32_dpp v86, v54 quad_perm:[1,0,3,2] row_mask:0xf bank_mask:0xf
	v_mov_b32_dpp v87, v38 quad_perm:[1,0,3,2] row_mask:0xf bank_mask:0xf
	v_mov_b32_dpp v88, v22 quad_perm:[1,0,3,2] row_mask:0xf bank_mask:0xf
	v_mov_b32_dpp v89, v6 quad_perm:[1,0,3,2] row_mask:0xf bank_mask:0xf
	v_mov_b32_dpp v90, v55 quad_perm:[1,0,3,2] row_mask:0xf bank_mask:0xf
	v_mov_b32_dpp v91, v39 quad_perm:[1,0,3,2] row_mask:0xf bank_mask:0xf
	v_mov_b32_dpp v92, v23 quad_perm:[1,0,3,2] row_mask:0xf bank_mask:0xf
	v_mov_b32_dpp v93, v7 quad_perm:[1,0,3,2] row_mask:0xf bank_mask:0xf
	v_cvt_pk_bf16_f32 v54, v54, v86
	v_cvt_pk_bf16_f32 v38, v38, v87
	v_cvt_pk_bf16_f32 v22, v22, v88
	v_cvt_pk_bf16_f32 v6, v6, v89
	v_cvt_pk_bf16_f32 v55, v55, v90
	v_cvt_pk_bf16_f32 v39, v39, v91
	v_cvt_pk_bf16_f32 v23, v23, v92
	v_cvt_pk_bf16_f32 v7, v7, v93
	v_mul_f32_e32 v56, v56, v76
	v_mul_f32_e32 v40, v40, v76
	v_mul_f32_e32 v24, v24, v76
	v_mul_f32_e32 v8, v8, v76
	v_mul_f32_e32 v57, v57, v77
	v_mul_f32_e32 v41, v41, v77
	v_mul_f32_e32 v25, v25, v77
	v_mul_f32_e32 v9, v9, v77
	v_mov_b32_dpp v86, v56 quad_perm:[1,0,3,2] row_mask:0xf bank_mask:0xf
; __device__ __forceinline__ int crow(int r, int hi) { return (r & 3) + 8 * (r >> 2) + 4 * hi; }
; __device__ __forceinline__ unsigned cvtpk(float lo, float hi) { unsigned r; asm volatile("v_cvt_pk_bf16_f32 %0, %1, %2" : "=v"(r) : "v"(lo), "v"(hi)); return r; }
; __device__ __forceinline__ void moba_block(const BlockRef& cur, const BlockRef& nxt, char* lds, Seam& S) {
;     ...
; #pragma unroll
;     for (int r = 0; r < 16; ++r) { const int orow = crow(r, hi);
; #pragma unroll
;         for (int d0 = 0; d0 < 4; ++d0) { const float v = o[d0][r] * rli[r];
;             const float vn = __shfl_xor(v, 1);
;             if ((r32 & 1) == 0) *(unsigned*)(Ow + (size_t)orow * OSTR + d0 * 32 + r32) = cvtpk(v, vn); } }
	v_mov_b32_dpp v87, v40 quad_perm:[1,0,3,2] row_mask:0xf bank_mask:0xf
	v_mov_b32_dpp v88, v24 quad_perm:[1,0,3,2] row_mask:0xf bank_mask:0xf
	v_mov_b32_dpp v89, v8 quad_perm:[1,0,3,2] row_mask:0xf bank_mask:0xf
	v_mov_b32_dpp v90, v57 quad_perm:[1,0,3,2] row_mask:0xf bank_mask:0xf
	v_mov_b32_dpp v91, v41 quad_perm:[1,0,3,2] row_mask:0xf bank_mask:0xf
	v_mov_b32_dpp v92, v25 quad_perm:[1,0,3,2] row_mask:0xf bank_mask:0xf
	v_mov_b32_dpp v93, v9 quad_perm:[1,0,3,2] row_mask:0xf bank_mask:0xf
	v_cvt_pk_bf16_f32 v56, v56, v86
	v_cvt_pk_bf16_f32 v40, v40, v87
	v_cvt_pk_bf16_f32 v24, v24, v88
	v_cvt_pk_bf16_f32 v8, v8, v89
	v_cvt_pk_bf16_f32 v57, v57, v90
	v_cvt_pk_bf16_f32 v41, v41, v91
	v_cvt_pk_bf16_f32 v25, v25, v92
	v_cvt_pk_bf16_f32 v9, v9, v93
	v_mul_f32_e32 v58, v58, v70
	v_mul_f32_e32 v42, v42, v70
	v_mul_f32_e32 v26, v26, v70
	v_mul_f32_e32 v10, v10, v70
	v_mul_f32_e32 v59, v59, v71
	v_mul_f32_e32 v43, v43, v71
	v_mul_f32_e32 v27, v27, v71
	v_mul_f32_e32 v11, v11, v71
	v_mov_b32_dpp v86, v58 quad_perm:[1,0,3,2] row_mask:0xf bank_mask:0xf
	v_mov_b32_dpp v87, v42 quad_perm:[1,0,3,2] row_mask:0xf bank_mask:0xf
	v_mov_b32_dpp v88, v26 quad_perm:[1,0,3,2] row_mask:0xf bank_mask:0xf
	v_mov_b32_dpp v89, v10 quad_perm:[1,0,3,2] row_mask:0xf bank_mask:0xf
	v_mov_b32_dpp v90, v59 quad_perm:[1,0,3,2] row_mask:0xf bank_mask:0xf
	v_mov_b32_dpp v91, v43 quad_perm:[1,0,3,2] row_mask:0xf bank_mask:0xf
	v_mov_b32_dpp v92, v27 quad_perm:[1,0,3,2] row_mask:0xf bank_mask:0xf
	v_mov_b32_dpp v93, v11 quad_perm:[1,0,3,2] row_mask:0xf bank_mask:0xf
	v_cvt_pk_bf16_f32 v58, v58, v86
	v_cvt_pk_bf16_f32 v42, v42, v87
	v_cvt_pk_bf16_f32 v26, v26, v88
	v_cvt_pk_bf16_f32 v10, v10, v89
	v_cvt_pk_bf16_f32 v59, v59, v90
	v_cvt_pk_bf16_f32 v43, v43, v91
	v_cvt_pk_bf16_f32 v27, v27, v92
	v_cvt_pk_bf16_f32 v11, v11, v93
	v_mul_f32_e32 v60, v60, v72
	v_mul_f32_e32 v44, v44, v72
	v_mul_f32_e32 v28, v28, v72
	v_mul_f32_e32 v12, v12, v72
	v_mul_f32_e32 v61, v61, v73
	v_mul_f32_e32 v45, v45, v73
	v_mul_f32_e32 v29, v29, v73
	v_mul_f32_e32 v13, v13, v73
	v_mov_b32_dpp v86, v60 quad_perm:[1,0,3,2] row_mask:0xf bank_mask:0xf
	v_mov_b32_dpp v87, v44 quad_perm:[1,0,3,2] row_mask:0xf bank_mask:0xf
	v_mov_b32_dpp v88, v28 quad_perm:[1,0,3,2] row_mask:0xf bank_mask:0xf
	v_mov_b32_dpp v89, v12 quad_perm:[1,0,3,2] row_mask:0xf bank_mask:0xf
	v_mov_b32_dpp v90, v61 quad_perm:[1,0,3,2] row_mask:0xf bank_mask:0xf
	v_mov_b32_dpp v91, v45 quad_perm:[1,0,3,2] row_mask:0xf bank_mask:0xf
	v_mov_b32_dpp v92, v29 quad_perm:[1,0,3,2] row_mask:0xf bank_mask:0xf
	v_mov_b32_dpp v93, v13 quad_perm:[1,0,3,2] row_mask:0xf bank_mask:0xf
	v_cvt_pk_bf16_f32 v60, v60, v86
	v_cvt_pk_bf16_f32 v44, v44, v87
	v_cvt_pk_bf16_f32 v28, v28, v88
	v_cvt_pk_bf16_f32 v12, v12, v89
	v_cvt_pk_bf16_f32 v61, v61, v90
	v_cvt_pk_bf16_f32 v45, v45, v91
	v_cvt_pk_bf16_f32 v29, v29, v92
	v_cvt_pk_bf16_f32 v13, v13, v93
	v_mul_f32_e32 v62, v62, v66
	v_mul_f32_e32 v46, v46, v66
	v_mul_f32_e32 v30, v30, v66
	v_mul_f32_e32 v14, v14, v66
	v_mul_f32_e32 v63, v63, v67
	v_mul_f32_e32 v47, v47, v67
	v_mul_f32_e32 v31, v31, v67
	v_mul_f32_e32 v15, v15, v67
	v_mov_b32_dpp v86, v62 quad_perm:[1,0,3,2] row_mask:0xf bank_mask:0xf
	v_mov_b32_dpp v87, v46 quad_perm:[1,0,3,2] row_mask:0xf bank_mask:0xf
	v_mov_b32_dpp v88, v30 quad_perm:[1,0,3,2] row_mask:0xf bank_mask:0xf
	v_mov_b32_dpp v89, v14 quad_perm:[1,0,3,2] row_mask:0xf bank_mask:0xf
	v_mov_b32_dpp v90, v63 quad_perm:[1,0,3,2] row_mask:0xf bank_mask:0xf
	v_mov_b32_dpp v91, v47 quad_perm:[1,0,3,2] row_mask:0xf bank_mask:0xf
	v_mov_b32_dpp v92, v31 quad_perm:[1,0,3,2] row_mask:0xf bank_mask:0xf
	v_mov_b32_dpp v93, v15 quad_perm:[1,0,3,2] row_mask:0xf bank_mask:0xf
	v_cvt_pk_bf16_f32 v62, v62, v86
	v_cvt_pk_bf16_f32 v46, v46, v87
	v_cvt_pk_bf16_f32 v30, v30, v88
	v_cvt_pk_bf16_f32 v14, v14, v89
	v_cvt_pk_bf16_f32 v63, v63, v90
	v_cvt_pk_bf16_f32 v47, v47, v91
	v_cvt_pk_bf16_f32 v31, v31, v92
	v_cvt_pk_bf16_f32 v15, v15, v93
	v_mul_f32_e32 v64, v64, v68
	v_mul_f32_e32 v48, v48, v68
	v_mul_f32_e32 v32, v32, v68
	v_mul_f32_e32 v16, v16, v68
	v_mul_f32_e32 v65, v65, v69
	v_mul_f32_e32 v49, v49, v69
	v_mul_f32_e32 v33, v33, v69
	v_mul_f32_e32 v17, v17, v69
	v_mov_b32_dpp v86, v64 quad_perm:[1,0,3,2] row_mask:0xf bank_mask:0xf
	v_mov_b32_dpp v87, v48 quad_perm:[1,0,3,2] row_mask:0xf bank_mask:0xf
	v_mov_b32_dpp v88, v32 quad_perm:[1,0,3,2] row_mask:0xf bank_mask:0xf
	v_mov_b32_dpp v89, v16 quad_perm:[1,0,3,2] row_mask:0xf bank_mask:0xf
; __device__ __forceinline__ int crow(int r, int hi) { return (r & 3) + 8 * (r >> 2) + 4 * hi; }
; __device__ __forceinline__ unsigned cvtpk(float lo, float hi) { unsigned r; asm volatile("v_cvt_pk_bf16_f32 %0, %1, %2" : "=v"(r) : "v"(lo), "v"(hi)); return r; }
; __device__ __forceinline__ void moba_block(const BlockRef& cur, const BlockRef& nxt, char* lds, Seam& S) {
;     ...
;     for (int r = 0; r < 16; ++r) { const int orow = crow(r, hi);
; #pragma unroll
;         for (int d0 = 0; d0 < 4; ++d0) { const float v = o[d0][r] * rli[r];
;             const float vn = __shfl_xor(v, 1);
;             if ((r32 & 1) == 0) *(unsigned*)(Ow + (size_t)orow * OSTR + d0 * 32 + r32) = cvtpk(v, vn); } }
	v_mov_b32_dpp v90, v65 quad_perm:[1,0,3,2] row_mask:0xf bank_mask:0xf
	v_mov_b32_dpp v91, v49 quad_perm:[1,0,3,2] row_mask:0xf bank_mask:0xf
	v_mov_b32_dpp v92, v33 quad_perm:[1,0,3,2] row_mask:0xf bank_mask:0xf
	v_mov_b32_dpp v93, v17 quad_perm:[1,0,3,2] row_mask:0xf bank_mask:0xf
	v_cvt_pk_bf16_f32 v64, v64, v86
	v_cvt_pk_bf16_f32 v48, v48, v87
	v_cvt_pk_bf16_f32 v32, v32, v88
	v_cvt_pk_bf16_f32 v16, v16, v89
	v_cvt_pk_bf16_f32 v65, v65, v90
	v_cvt_pk_bf16_f32 v49, v49, v91
	v_cvt_pk_bf16_f32 v33, v33, v92
	v_cvt_pk_bf16_f32 v17, v17, v93
	s_and_saveexec_b64 s[0:1], s[38:39]
	global_store_dword v[82:83], v50, off sc1
	global_store_dword v[82:83], v34, off offset:64 sc1
	global_store_dword v[82:83], v18, off offset:128 sc1
	global_store_dword v[82:83], v2, off offset:192 sc1
	global_store_dword v[82:83], v51, off offset:2048 sc1
	global_store_dword v[82:83], v35, off offset:2112 sc1
	global_store_dword v[82:83], v19, off offset:2176 sc1
	global_store_dword v[82:83], v3, off offset:2240 sc1
	s_mov_b64 vcc, 0x1000
	v_lshl_add_u64 v[84:85], v[82:83], 0, vcc
	global_store_dword v[84:85], v52, off sc1
	global_store_dword v[84:85], v36, off offset:64 sc1
	global_store_dword v[84:85], v20, off offset:128 sc1
	global_store_dword v[84:85], v4, off offset:192 sc1
	global_store_dword v[84:85], v53, off offset:2048 sc1
	global_store_dword v[84:85], v37, off offset:2112 sc1
	global_store_dword v[84:85], v21, off offset:2176 sc1
	global_store_dword v[84:85], v5, off offset:2240 sc1
	s_mov_b64 vcc, 0x4000
	v_lshl_add_u64 v[84:85], v[82:83], 0, vcc
	global_store_dword v[84:85], v54, off sc1
	global_store_dword v[84:85], v38, off offset:64 sc1
	global_store_dword v[84:85], v22, off offset:128 sc1
	global_store_dword v[84:85], v6, off offset:192 sc1
	global_store_dword v[84:85], v55, off offset:2048 sc1
	global_store_dword v[84:85], v39, off offset:2112 sc1
	global_store_dword v[84:85], v23, off offset:2176 sc1
	global_store_dword v[84:85], v7, off offset:2240 sc1
	s_mov_b64 vcc, 0x5000
	v_lshl_add_u64 v[84:85], v[82:83], 0, vcc
	global_store_dword v[84:85], v56, off sc1
	global_store_dword v[84:85], v40, off offset:64 sc1
	global_store_dword v[84:85], v24, off offset:128 sc1
	global_store_dword v[84:85], v8, off offset:192 sc1
	global_store_dword v[84:85], v57, off offset:2048 sc1
	global_store_dword v[84:85], v41, off offset:2112 sc1
	global_store_dword v[84:85], v25, off offset:2176 sc1
	global_store_dword v[84:85], v9, off offset:2240 sc1
	s_mov_b64 vcc, 0x8000
	v_lshl_add_u64 v[84:85], v[82:83], 0, vcc
	global_store_dword v[84:85], v58, off sc1
	global_store_dword v[84:85], v42, off offset:64 sc1
	global_store_dword v[84:85], v26, off offset:128 sc1
	global_store_dword v[84:85], v10, off offset:192 sc1
	global_store_dword v[84:85], v59, off offset:2048 sc1
	global_store_dword v[84:85], v43, off offset:2112 sc1
	global_store_dword v[84:85], v27, off offset:2176 sc1
	global_store_dword v[84:85], v11, off offset:2240 sc1
	s_mov_b64 vcc, 0x9000
	v_lshl_add_u64 v[84:85], v[82:83], 0, vcc
	global_store_dword v[84:85], v60, off sc1
	global_store_dword v[84:85], v44, off offset:64 sc1
	global_store_dword v[84:85], v28, off offset:128 sc1
	global_store_dword v[84:85], v12, off offset:192 sc1
	global_store_dword v[84:85], v61, off offset:2048 sc1
	global_store_dword v[84:85], v45, off offset:2112 sc1
	global_store_dword v[84:85], v29, off offset:2176 sc1
	global_store_dword v[84:85], v13, off offset:2240 sc1
	s_mov_b64 vcc, 0xc000
	v_lshl_add_u64 v[84:85], v[82:83], 0, vcc
	global_store_dword v[84:85], v62, off sc1
	global_store_dword v[84:85], v46, off offset:64 sc1
	global_store_dword v[84:85], v30, off offset:128 sc1
	global_store_dword v[84:85], v14, off offset:192 sc1
	global_store_dword v[84:85], v63, off offset:2048 sc1
	global_store_dword v[84:85], v47, off offset:2112 sc1
	global_store_dword v[84:85], v31, off offset:2176 sc1
	global_store_dword v[84:85], v15, off offset:2240 sc1
	s_mov_b64 vcc, 0xd000
	v_lshl_add_u64 v[84:85], v[82:83], 0, vcc
	global_store_dword v[84:85], v64, off sc1
	global_store_dword v[84:85], v48, off offset:64 sc1
	global_store_dword v[84:85], v32, off offset:128 sc1
	global_store_dword v[84:85], v16, off offset:192 sc1
	global_store_dword v[84:85], v65, off offset:2048 sc1
	global_store_dword v[84:85], v49, off offset:2112 sc1
	global_store_dword v[84:85], v33, off offset:2176 sc1
	global_store_dword v[84:85], v17, off offset:2240 sc1
	s_or_b64 exec, exec, s[0:1]
